# GLA gate, cq and ckv row loops hand-written: hoisted gain vectors, A/B prefetch sets, counted vmcnt, DPP reductions
# speedup vs baseline: 1.0049x; 1.0049x over previous
.LBB0_61:
	global_load_dwordx2 v[30:31], v[0:1], off
	global_load_dwordx2 v[32:33], v[0:1], off offset:512
	global_load_dwordx2 v[34:35], v[0:1], off offset:1024
	v_and_b32_e32 v40, 63, v220
	v_lshrrev_b32_e32 v42, 6, v220
	v_lshlrev_b32_e32 v41, 2, v40
	v_lshlrev_b32_e32 v40, 3, v40
	v_readfirstlane_b32 s14, v42
	s_lshl_b32 s15, s2, 3
	s_nop 3
	s_add_i32 s24, s15, s14
	s_lshl_b32 s25, s94, 3
	v_readlane_b32 s16, v253, 58
	v_readlane_b32 s17, v253, 59
	v_readlane_b32 s38, v253, 60
	v_readlane_b32 s39, v253, 61
	s_nop 1
	s_lshl_b32 s14, s24, 11
	s_add_u32 s40, s16, s14
	s_addc_u32 s41, s17, 0
	global_load_dwordx2 v[6:7], v40, s[40:41] offset:-512
	global_load_dwordx2 v[8:9], v40, s[40:41]
	global_load_dwordx2 v[10:11], v40, s[40:41] offset:512
	s_mov_b32 s5, 1
.Lcq_loop:
	s_add_i32 s28, s24, s25
	s_cmp_lt_u32 s28, 0x8000
	s_cbranch_scc0 .Lcq_nopf_A
	s_lshl_b32 s14, s28, 11
	s_add_u32 s40, s16, s14
	s_addc_u32 s41, s17, 0
	global_load_dwordx2 v[12:13], v40, s[40:41] offset:-512
	global_load_dwordx2 v[14:15], v40, s[40:41]
	global_load_dwordx2 v[16:17], v40, s[40:41] offset:512
	s_cmp_eq_u32 s5, 0
	s_cbranch_scc1 .Lcq_rel_A
	s_mov_b32 s5, 0
	s_waitcnt vmcnt(3)
	s_branch .Lcq_go_A
.Lcq_rel_A:
	s_waitcnt vmcnt(6)
	s_branch .Lcq_go_A

.Lcq_go_A:
	v_mul_f32_e32 v20, v6, v6
	v_mul_f32_e32 v21, v7, v7
	v_fmac_f32_e32 v20, v8, v8
	v_fmac_f32_e32 v21, v9, v9
	v_fmac_f32_e32 v20, v10, v10
	v_fmac_f32_e32 v21, v11, v11
	v_add_f32_e32 v20, v20, v21
	s_nop 1
	v_add_f32_dpp v20, v20, v20 quad_perm:[1,0,3,2] row_mask:0xf bank_mask:0xf
	s_nop 1
	v_add_f32_dpp v20, v20, v20 quad_perm:[2,3,0,1] row_mask:0xf bank_mask:0xf
	s_nop 1
	v_add_f32_dpp v20, v20, v20 row_half_mirror row_mask:0xf bank_mask:0xf
	s_nop 1
	v_add_f32_dpp v20, v20, v20 row_mirror row_mask:0xf bank_mask:0xf
	s_nop 1
	v_readlane_b32 s14, v20, 0
	v_readlane_b32 s15, v20, 16
	v_readlane_b32 s29, v20, 32
	v_readlane_b32 s10, v20, 48
	s_nop 1
	v_mov_b32_e32 v21, s14
	v_add_f32_e32 v21, s15, v21
	v_add_f32_e32 v21, s29, v21
	v_add_f32_e32 v21, s10, v21
	v_fmamk_f32 v21, v21, 0x3b2aaaab, v221
	v_rsq_f32_e32 v21, v21
	s_nop 0
	v_mul_f32_e32 v6, v6, v21
	v_mul_f32_e32 v6, v30, v6
	v_mul_f32_e32 v7, v7, v21
	v_mul_f32_e32 v7, v31, v7
	v_mul_f32_e32 v8, v8, v21
	v_mul_f32_e32 v8, v32, v8
	v_mul_f32_e32 v9, v9, v21
	v_mul_f32_e32 v9, v33, v9
	v_mul_f32_e32 v10, v10, v21
	v_mul_f32_e32 v10, v34, v10
	v_mul_f32_e32 v11, v11, v21
	v_mul_f32_e32 v11, v35, v11
	v_cvt_pk_bf16_f32 v24, v6, v7
	v_cvt_pk_bf16_f32 v25, v8, v9
	v_cvt_pk_bf16_f32 v26, v10, v11
	s_mul_i32 s14, s24, 0x300
	s_add_u32 s40, s38, s14
	s_addc_u32 s41, s39, 0
	global_store_dword v41, v24, s[40:41] offset:-256
	global_store_dword v41, v25, s[40:41]
	global_store_dword v41, v26, s[40:41] offset:256
	s_cmp_lt_u32 s28, 0x8000
	s_cbranch_scc0 .Lcq_done
	s_mov_b32 s24, s28
	s_add_i32 s28, s24, s25
	s_cmp_lt_u32 s28, 0x8000
	s_cbranch_scc0 .Lcq_nopf_B
	s_lshl_b32 s14, s28, 11
	s_add_u32 s40, s16, s14
	s_addc_u32 s41, s17, 0
	global_load_dwordx2 v[6:7], v40, s[40:41] offset:-512
	global_load_dwordx2 v[8:9], v40, s[40:41]
	global_load_dwordx2 v[10:11], v40, s[40:41] offset:512
	s_cmp_eq_u32 s5, 0
	s_cbranch_scc1 .Lcq_rel_B
	s_mov_b32 s5, 0
	s_waitcnt vmcnt(3)
	s_branch .Lcq_go_B

.Lcq_go_B:
	v_mul_f32_e32 v20, v12, v12
	v_mul_f32_e32 v21, v13, v13
	v_fmac_f32_e32 v20, v14, v14
	v_fmac_f32_e32 v21, v15, v15
	v_fmac_f32_e32 v20, v16, v16
	v_fmac_f32_e32 v21, v17, v17
	v_add_f32_e32 v20, v20, v21
	s_nop 1
	v_add_f32_dpp v20, v20, v20 quad_perm:[1,0,3,2] row_mask:0xf bank_mask:0xf
	s_nop 1
	v_add_f32_dpp v20, v20, v20 quad_perm:[2,3,0,1] row_mask:0xf bank_mask:0xf
	s_nop 1
	v_add_f32_dpp v20, v20, v20 row_half_mirror row_mask:0xf bank_mask:0xf
	s_nop 1
	v_add_f32_dpp v20, v20, v20 row_mirror row_mask:0xf bank_mask:0xf
	s_nop 1
	v_readlane_b32 s14, v20, 0
	v_readlane_b32 s15, v20, 16
	v_readlane_b32 s29, v20, 32
	v_readlane_b32 s10, v20, 48
	s_nop 1
	v_mov_b32_e32 v21, s14
	v_add_f32_e32 v21, s15, v21
	v_add_f32_e32 v21, s29, v21
	v_add_f32_e32 v21, s10, v21
	v_fmamk_f32 v21, v21, 0x3b2aaaab, v221
	v_rsq_f32_e32 v21, v21
	s_nop 0
	v_mul_f32_e32 v12, v12, v21
	v_mul_f32_e32 v12, v30, v12
	v_mul_f32_e32 v13, v13, v21
	v_mul_f32_e32 v13, v31, v13
	v_mul_f32_e32 v14, v14, v21
	v_mul_f32_e32 v14, v32, v14
	v_mul_f32_e32 v15, v15, v21
	v_mul_f32_e32 v15, v33, v15
	v_mul_f32_e32 v16, v16, v21
	v_mul_f32_e32 v16, v34, v16
	v_mul_f32_e32 v17, v17, v21
	v_mul_f32_e32 v17, v35, v17
	v_cvt_pk_bf16_f32 v24, v12, v13
	v_cvt_pk_bf16_f32 v25, v14, v15
	v_cvt_pk_bf16_f32 v26, v16, v17
	s_mul_i32 s14, s24, 0x300
	s_add_u32 s40, s38, s14
	s_addc_u32 s41, s39, 0
	global_store_dword v41, v24, s[40:41] offset:-256
	global_store_dword v41, v25, s[40:41]
	global_store_dword v41, v26, s[40:41] offset:256
	s_cmp_lt_u32 s28, 0x8000
	s_cbranch_scc0 .Lcq_done
	s_mov_b32 s24, s28
	s_branch .Lcq_loop
.Lcq_done:
	s_mov_b64 s[0:1], exec

.LBB0_106:
.LBB0_107:
	s_mov_b64 exec, -1
	global_load_dwordx4 v[40:43], v[0:1], off
	v_and_b32_e32 v49, 63, v220
	v_lshrrev_b32_e32 v44, 6, v220
	v_lshlrev_b32_e32 v48, 4, v49
	v_lshlrev_b32_e32 v50, 3, v49
	v_lshlrev_b32_e32 v51, 1, v49
	v_lshlrev_b32_e32 v49, 2, v49
	v_readfirstlane_b32 s0, v44
	s_lshl_b32 s1, s2, 3
	s_nop 3
	s_add_i32 s24, s1, s0
	s_lshl_b32 s25, s94, 3
	s_lshl_b32 s14, s24, 11
	s_add_u32 s14, s14, 0x7dc4000
	s_add_u32 s14, s20, s14
	s_addc_u32 s15, s21, 0
	global_load_dwordx4 v[20:23], v48, s[14:15]
	global_load_dword v24, v49, s[14:15] offset:1024
	global_load_dword v25, v49, s[14:15] offset:1152
	s_lshl_b32 s14, s24, 7
	s_add_u32 s14, s14, 0x1fc4000
	s_add_u32 s14, s20, s14
	s_addc_u32 s15, s21, 0
	global_load_dword v26, v49, s[14:15]
	s_lshl_b32 s14, s24, 7
	s_add_u32 s14, s14, 0x23c4000
	s_add_u32 s14, s20, s14
	s_addc_u32 s15, s21, 0
	global_load_dword v27, v49, s[14:15]
	s_mov_b32 s39, 1
.Lkv_loop:
	s_add_i32 s38, s24, s25
	s_cmp_lt_u32 s38, 0x8000
	s_cbranch_scc0 .Lkv_nopf_A
	s_lshl_b32 s14, s38, 11
	s_add_u32 s14, s14, 0x7dc4000
	s_add_u32 s14, s20, s14
	s_addc_u32 s15, s21, 0
	global_load_dwordx4 v[30:33], v48, s[14:15]
	global_load_dword v34, v49, s[14:15] offset:1024
	global_load_dword v35, v49, s[14:15] offset:1152
	s_lshl_b32 s14, s38, 7
	s_add_u32 s14, s14, 0x1fc4000
	s_add_u32 s14, s20, s14
	s_addc_u32 s15, s21, 0
	global_load_dword v36, v49, s[14:15]
	s_lshl_b32 s14, s38, 7
	s_add_u32 s14, s14, 0x23c4000
	s_add_u32 s14, s20, s14
	s_addc_u32 s15, s21, 0
	global_load_dword v37, v49, s[14:15]
	s_cmp_eq_u32 s39, 0
	s_cbranch_scc1 .Lkv_rel_A
	s_mov_b32 s39, 0
	s_waitcnt vmcnt(5)
	s_branch .Lkv_go_A

.Lkv_go_A:
	v_mul_f32_e32 v44, v20, v20
	v_mul_f32_e32 v45, v21, v21
	v_fmac_f32_e32 v44, v22, v22
	v_fmac_f32_e32 v45, v23, v23
	v_add_f32_e32 v44, v44, v45
	s_nop 1
	v_add_f32_dpp v44, v44, v44 quad_perm:[1,0,3,2] row_mask:0xf bank_mask:0xf
	s_nop 1
	v_add_f32_dpp v44, v44, v44 quad_perm:[2,3,0,1] row_mask:0xf bank_mask:0xf
	s_nop 1
	v_add_f32_dpp v44, v44, v44 row_half_mirror row_mask:0xf bank_mask:0xf
	s_nop 1
	v_add_f32_dpp v44, v44, v44 row_mirror row_mask:0xf bank_mask:0xf
	s_nop 1
	v_readlane_b32 s0, v44, 0
	v_readlane_b32 s1, v44, 16
	v_readlane_b32 s16, v44, 32
	v_readlane_b32 s17, v44, 48
	s_nop 1
	v_mov_b32_e32 v45, s0
	v_add_f32_e32 v45, s1, v45
	v_add_f32_e32 v45, s16, v45
	v_add_f32_e32 v45, s17, v45
	v_fmamk_f32 v45, v45, 0x3b800000, v221
	v_rsq_f32_e32 v45, v45
	s_nop 0
	v_mul_f32_e32 v20, v20, v45
	v_mul_f32_e32 v20, v40, v20
	v_mul_f32_e32 v21, v21, v45
	v_mul_f32_e32 v21, v41, v21
	v_mul_f32_e32 v22, v22, v45
	v_mul_f32_e32 v22, v42, v22
	v_mul_f32_e32 v23, v23, v45
	v_mul_f32_e32 v23, v43, v23
	v_cvt_pk_bf16_f32 v52, v20, v21
	v_cvt_pk_bf16_f32 v53, v22, v23
	v_mul_f32_e32 v44, v25, v27
	v_mul_f32_e32 v45, v24, v27
	v_fma_f32 v44, v24, v26, -v44
	v_fmac_f32_e32 v45, v25, v26
	v_cvt_pk_bf16_f32 v54, v44, s0
	v_cvt_pk_bf16_f32 v55, v45, s0
	s_lshl_b32 s14, s24, 9
	s_add_u32 s14, s14, 0x29c4000
	s_add_u32 s14, s20, s14
	s_addc_u32 s15, s21, 0
	global_store_dwordx2 v50, v[52:53], s[14:15]
	s_lshl_b32 s14, s24, 7
	s_add_u32 s14, s14, 0x39c4000
	s_add_u32 s14, s20, s14
	s_addc_u32 s15, s21, 0
	s_mov_b32 exec_hi, 0
	global_store_short v51, v54, s[14:15]
	global_store_short v51, v55, s[14:15] offset:64
	s_mov_b32 exec_hi, -1
	s_cmp_lt_u32 s38, 0x8000
	s_cbranch_scc0 .Lkv_done
	s_mov_b32 s24, s38
	s_add_i32 s38, s24, s25
	s_cmp_lt_u32 s38, 0x8000
	s_cbranch_scc0 .Lkv_nopf_B
	s_lshl_b32 s14, s38, 11
	s_add_u32 s14, s14, 0x7dc4000
	s_add_u32 s14, s20, s14
	s_addc_u32 s15, s21, 0
	global_load_dwordx4 v[20:23], v48, s[14:15]
	global_load_dword v24, v49, s[14:15] offset:1024
	global_load_dword v25, v49, s[14:15] offset:1152
	s_lshl_b32 s14, s38, 7
	s_add_u32 s14, s14, 0x1fc4000
	s_add_u32 s14, s20, s14
	s_addc_u32 s15, s21, 0
	global_load_dword v26, v49, s[14:15]
	s_lshl_b32 s14, s38, 7
	s_add_u32 s14, s14, 0x23c4000
	s_add_u32 s14, s20, s14
	s_addc_u32 s15, s21, 0
	global_load_dword v27, v49, s[14:15]
	s_cmp_eq_u32 s39, 0
	s_cbranch_scc1 .Lkv_rel_B
	s_mov_b32 s39, 0
	s_waitcnt vmcnt(5)
	s_branch .Lkv_go_B

.Lkv_go_B:
	v_mul_f32_e32 v44, v30, v30
	v_mul_f32_e32 v45, v31, v31
	v_fmac_f32_e32 v44, v32, v32
	v_fmac_f32_e32 v45, v33, v33
	v_add_f32_e32 v44, v44, v45
	s_nop 1
	v_add_f32_dpp v44, v44, v44 quad_perm:[1,0,3,2] row_mask:0xf bank_mask:0xf
	s_nop 1
	v_add_f32_dpp v44, v44, v44 quad_perm:[2,3,0,1] row_mask:0xf bank_mask:0xf
	s_nop 1
	v_add_f32_dpp v44, v44, v44 row_half_mirror row_mask:0xf bank_mask:0xf
	s_nop 1
	v_add_f32_dpp v44, v44, v44 row_mirror row_mask:0xf bank_mask:0xf
	s_nop 1
	v_readlane_b32 s0, v44, 0
	v_readlane_b32 s1, v44, 16
	v_readlane_b32 s16, v44, 32
	v_readlane_b32 s17, v44, 48
	s_nop 1
	v_mov_b32_e32 v45, s0
	v_add_f32_e32 v45, s1, v45
	v_add_f32_e32 v45, s16, v45
	v_add_f32_e32 v45, s17, v45
	v_fmamk_f32 v45, v45, 0x3b800000, v221
	v_rsq_f32_e32 v45, v45
	s_nop 0
	v_mul_f32_e32 v30, v30, v45
	v_mul_f32_e32 v30, v40, v30
	v_mul_f32_e32 v31, v31, v45
	v_mul_f32_e32 v31, v41, v31
	v_mul_f32_e32 v32, v32, v45
	v_mul_f32_e32 v32, v42, v32
	v_mul_f32_e32 v33, v33, v45
	v_mul_f32_e32 v33, v43, v33
	v_cvt_pk_bf16_f32 v52, v30, v31
	v_cvt_pk_bf16_f32 v53, v32, v33
	v_mul_f32_e32 v44, v35, v37
	v_mul_f32_e32 v45, v34, v37
	v_fma_f32 v44, v34, v36, -v44
	v_fmac_f32_e32 v45, v35, v36
	v_cvt_pk_bf16_f32 v54, v44, s0
	v_cvt_pk_bf16_f32 v55, v45, s0
	s_lshl_b32 s14, s24, 9
	s_add_u32 s14, s14, 0x29c4000
	s_add_u32 s14, s20, s14
	s_addc_u32 s15, s21, 0
	global_store_dwordx2 v50, v[52:53], s[14:15]
	s_lshl_b32 s14, s24, 7
	s_add_u32 s14, s14, 0x39c4000
	s_add_u32 s14, s20, s14
	s_addc_u32 s15, s21, 0
	s_mov_b32 exec_hi, 0
	global_store_short v51, v54, s[14:15]
	global_store_short v51, v55, s[14:15] offset:64
	s_mov_b32 exec_hi, -1
	s_cmp_lt_u32 s38, 0x8000
	s_cbranch_scc0 .Lkv_done
	s_mov_b32 s24, s38
	s_branch .Lkv_loop
.Lkv_done:
.LBB0_109:
	s_or_b64 exec, exec, s[28:29]
	s_mov_b64 s[0:1], 0
	s_mov_b64 s[84:85], -1

.LBB0_144:
	s_movk_i32 s10, 0x1a00
	s_mov_b32 s13, 0x10000
	s_movk_i32 s69, 0x2000
	s_movk_i32 s16, 0x1000
	s_mov_b32 s54, 0xfdc4000
	s_mov_b32 s17, 0xbfb8aa3b
	s_mov_b32 s18, 0x1cdc4000
	s_mov_b32 s19, 0x3f317217
	s_mov_b32 s68, 0x3db504f3
	s_and_b64 vcc, exec, s[0:1]
	s_cbranch_vccz .LBB0_197
	s_cmp_lt_i32 s22, 7
	s_mov_b64 s[0:1], -1
	s_cbranch_scc1 .LBB0_177
	s_cmp_gt_i32 s22, 7
	s_cbranch_scc0 .LBB0_153
	s_mov_b64 s[38:39], exec
	v_and_b32_e32 v100, 63, v220
	v_lshrrev_b32_e32 v96, 6, v220
	v_and_b32_e32 v97, 15, v220
	v_lshlrev_b32_e32 v100, 5, v100
	v_lshlrev_b32_e32 v97, 6, v97
	v_readfirstlane_b32 s0, v96
	s_lshl_b32 s1, s2, 3
	s_nop 3
	s_add_i32 s24, s1, s0
	s_lshl_b32 s25, s94, 3
	v_readlane_b32 s14, v251, 8
	v_readlane_b32 s15, v251, 9
	v_readlane_b32 s40, v254, 17
	v_readlane_b32 s41, v254, 18
	s_nop 4
	global_load_dwordx4 v[80:83], v97, s[40:41] offset:0
	global_load_dwordx4 v[84:87], v97, s[40:41] offset:16
	global_load_dwordx4 v[88:91], v97, s[40:41] offset:32
	global_load_dwordx4 v[92:95], v97, s[40:41] offset:48
	s_lshl_b32 s0, s24, 11
	s_add_u32 s40, s14, s0
	s_addc_u32 s41, s15, 0
	global_load_dwordx4 v[0:3], v100, s[40:41]
	global_load_dwordx4 v[4:7], v100, s[40:41] offset:16
	s_mul_i32 s0, s24, 0x1a00
	s_add_u32 s40, s96, s0
	s_addc_u32 s41, s97, 0
	global_load_dwordx4 v[8:11], v100, s[40:41]
	global_load_dwordx4 v[12:15], v100, s[40:41] offset:16
	s_add_u32 s40, s40, 0x1000
	s_addc_u32 s41, s41, 0
	global_load_dwordx4 v[16:19], v100, s[40:41]
	global_load_dwordx4 v[20:23], v100, s[40:41] offset:16
	s_mov_b32 s29, 1
.Lgt_loop:
	s_add_i32 s28, s24, s25
	s_cmp_lt_u32 s28, 0x8000
	s_cbranch_scc0 .Lgt_nopf_A
	s_lshl_b32 s0, s28, 11
	s_add_u32 s40, s14, s0
	s_addc_u32 s41, s15, 0
	global_load_dwordx4 v[24:27], v100, s[40:41]
	global_load_dwordx4 v[28:31], v100, s[40:41] offset:16
	s_mul_i32 s0, s28, 0x1a00
	s_add_u32 s40, s96, s0
	s_addc_u32 s41, s97, 0
	global_load_dwordx4 v[32:35], v100, s[40:41]
	global_load_dwordx4 v[36:39], v100, s[40:41] offset:16
	s_add_u32 s40, s40, 0x1000
	s_addc_u32 s41, s41, 0
	global_load_dwordx4 v[40:43], v100, s[40:41]
	global_load_dwordx4 v[44:47], v100, s[40:41] offset:16
	s_cmp_eq_u32 s29, 0
	s_cbranch_scc1 .Lgt_rel_A
	s_mov_b32 s29, 0
	s_waitcnt vmcnt(6)
	s_branch .Lgt_go_A

.Lgt_go_A:
	v_lshlrev_b32_e32 v48, 16, v0
	v_lshlrev_b32_e32 v96, 16, v8
	v_add_f32_e32 v48, v48, v96
	v_and_b32_e32 v49, 0xffff0000, v0
	v_and_b32_e32 v97, 0xffff0000, v8
	v_add_f32_e32 v49, v49, v97
	v_lshlrev_b32_e32 v50, 16, v1
	v_lshlrev_b32_e32 v96, 16, v9
	v_add_f32_e32 v50, v50, v96
	v_and_b32_e32 v51, 0xffff0000, v1
	v_and_b32_e32 v97, 0xffff0000, v9
	v_add_f32_e32 v51, v51, v97
	v_lshlrev_b32_e32 v52, 16, v2
	v_lshlrev_b32_e32 v96, 16, v10
	v_add_f32_e32 v52, v52, v96
	v_and_b32_e32 v53, 0xffff0000, v2
	v_and_b32_e32 v97, 0xffff0000, v10
	v_add_f32_e32 v53, v53, v97
	v_lshlrev_b32_e32 v54, 16, v3
	v_lshlrev_b32_e32 v96, 16, v11
	v_add_f32_e32 v54, v54, v96
	v_and_b32_e32 v55, 0xffff0000, v3
	v_and_b32_e32 v97, 0xffff0000, v11
	v_add_f32_e32 v55, v55, v97
	v_lshlrev_b32_e32 v56, 16, v4
	v_lshlrev_b32_e32 v96, 16, v12
	v_add_f32_e32 v56, v56, v96
	v_and_b32_e32 v57, 0xffff0000, v4
	v_and_b32_e32 v97, 0xffff0000, v12
	v_add_f32_e32 v57, v57, v97
	v_lshlrev_b32_e32 v58, 16, v5
	v_lshlrev_b32_e32 v96, 16, v13
	v_add_f32_e32 v58, v58, v96
	v_and_b32_e32 v59, 0xffff0000, v5
	v_and_b32_e32 v97, 0xffff0000, v13
	v_add_f32_e32 v59, v59, v97
	v_lshlrev_b32_e32 v60, 16, v6
	v_lshlrev_b32_e32 v96, 16, v14
	v_add_f32_e32 v60, v60, v96
	v_and_b32_e32 v61, 0xffff0000, v6
	v_and_b32_e32 v97, 0xffff0000, v14
	v_add_f32_e32 v61, v61, v97
	v_lshlrev_b32_e32 v62, 16, v7
	v_lshlrev_b32_e32 v96, 16, v15
	v_add_f32_e32 v62, v62, v96
	v_and_b32_e32 v63, 0xffff0000, v7
	v_and_b32_e32 v97, 0xffff0000, v15
	v_add_f32_e32 v63, v63, v97
	v_lshlrev_b32_e32 v64, 16, v16
	v_and_b32_e32 v65, 0xffff0000, v16
	v_lshlrev_b32_e32 v66, 16, v17
	v_and_b32_e32 v67, 0xffff0000, v17
	v_lshlrev_b32_e32 v68, 16, v18
	v_and_b32_e32 v69, 0xffff0000, v18
	v_lshlrev_b32_e32 v70, 16, v19
	v_and_b32_e32 v71, 0xffff0000, v19
	v_lshlrev_b32_e32 v72, 16, v20
	v_and_b32_e32 v73, 0xffff0000, v20
	v_lshlrev_b32_e32 v74, 16, v21
	v_and_b32_e32 v75, 0xffff0000, v21
	v_lshlrev_b32_e32 v76, 16, v22
	v_and_b32_e32 v77, 0xffff0000, v22
	v_lshlrev_b32_e32 v78, 16, v23
	v_and_b32_e32 v79, 0xffff0000, v23
	v_mul_f32_e32 v96, v48, v48
	v_mul_f32_e32 v97, v49, v49
	v_fmac_f32_e32 v96, v50, v50
	v_fmac_f32_e32 v97, v51, v51
	v_fmac_f32_e32 v96, v52, v52
	v_fmac_f32_e32 v97, v53, v53
	v_fmac_f32_e32 v96, v54, v54
	v_fmac_f32_e32 v97, v55, v55
	v_fmac_f32_e32 v96, v56, v56
	v_fmac_f32_e32 v97, v57, v57
	v_fmac_f32_e32 v96, v58, v58
	v_fmac_f32_e32 v97, v59, v59
	v_fmac_f32_e32 v96, v60, v60
	v_fmac_f32_e32 v97, v61, v61
	v_fmac_f32_e32 v96, v62, v62
	v_fmac_f32_e32 v97, v63, v63
	v_add_f32_e32 v96, v96, v97
	s_nop 1
	v_add_f32_dpp v96, v96, v96 quad_perm:[1,0,3,2] row_mask:0xf bank_mask:0xf
	s_nop 1
	v_add_f32_dpp v96, v96, v96 quad_perm:[2,3,0,1] row_mask:0xf bank_mask:0xf
	s_nop 1
	v_add_f32_dpp v96, v96, v96 row_half_mirror row_mask:0xf bank_mask:0xf
	s_nop 1
	v_add_f32_dpp v96, v96, v96 row_mirror row_mask:0xf bank_mask:0xf
	v_fmamk_f32 v96, v96, 0x3b800000, v221
	v_rsq_f32_e32 v96, v96
	v_mul_f32_e32 v104, 0xbfb8aa3b, v64
	v_mul_f32_e32 v105, 0xbfb8aa3b, v65
	v_mul_f32_e32 v106, 0xbfb8aa3b, v66
	v_mul_f32_e32 v107, 0xbfb8aa3b, v67
	v_mul_f32_e32 v108, 0xbfb8aa3b, v68
	v_mul_f32_e32 v109, 0xbfb8aa3b, v69
	v_mul_f32_e32 v110, 0xbfb8aa3b, v70
	v_mul_f32_e32 v111, 0xbfb8aa3b, v71
	v_exp_f32_e32 v104, v104
	v_exp_f32_e32 v105, v105
	v_exp_f32_e32 v106, v106
	v_exp_f32_e32 v107, v107
	v_exp_f32_e32 v108, v108
	v_exp_f32_e32 v109, v109
	v_exp_f32_e32 v110, v110
	v_exp_f32_e32 v111, v111
	v_add_f32_e32 v104, 1.0, v104
	v_add_f32_e32 v105, 1.0, v105
	v_add_f32_e32 v106, 1.0, v106
	v_add_f32_e32 v107, 1.0, v107
	v_add_f32_e32 v108, 1.0, v108
	v_add_f32_e32 v109, 1.0, v109
	v_add_f32_e32 v110, 1.0, v110
	v_add_f32_e32 v111, 1.0, v111
	v_rcp_f32_e32 v104, v104
	v_rcp_f32_e32 v105, v105
	v_rcp_f32_e32 v106, v106
	v_rcp_f32_e32 v107, v107
	v_rcp_f32_e32 v108, v108
	v_rcp_f32_e32 v109, v109
	v_rcp_f32_e32 v110, v110
	v_rcp_f32_e32 v111, v111
	v_mul_f32_e32 v64, v64, v104
	v_mul_f32_e32 v65, v65, v105
	v_mul_f32_e32 v66, v66, v106
	v_mul_f32_e32 v67, v67, v107
	v_mul_f32_e32 v68, v68, v108
	v_mul_f32_e32 v69, v69, v109
	v_mul_f32_e32 v70, v70, v110
	v_mul_f32_e32 v71, v71, v111
	v_mul_f32_e32 v104, 0xbfb8aa3b, v72
	v_mul_f32_e32 v105, 0xbfb8aa3b, v73
	v_mul_f32_e32 v106, 0xbfb8aa3b, v74
	v_mul_f32_e32 v107, 0xbfb8aa3b, v75
	v_mul_f32_e32 v108, 0xbfb8aa3b, v76
	v_mul_f32_e32 v109, 0xbfb8aa3b, v77
	v_mul_f32_e32 v110, 0xbfb8aa3b, v78
	v_mul_f32_e32 v111, 0xbfb8aa3b, v79
	v_exp_f32_e32 v104, v104
	v_exp_f32_e32 v105, v105
	v_exp_f32_e32 v106, v106
	v_exp_f32_e32 v107, v107
	v_exp_f32_e32 v108, v108
	v_exp_f32_e32 v109, v109
	v_exp_f32_e32 v110, v110
	v_exp_f32_e32 v111, v111
	v_add_f32_e32 v104, 1.0, v104
	v_add_f32_e32 v105, 1.0, v105
	v_add_f32_e32 v106, 1.0, v106
	v_add_f32_e32 v107, 1.0, v107
	v_add_f32_e32 v108, 1.0, v108
	v_add_f32_e32 v109, 1.0, v109
	v_add_f32_e32 v110, 1.0, v110
	v_add_f32_e32 v111, 1.0, v111
	v_rcp_f32_e32 v104, v104
	v_rcp_f32_e32 v105, v105
	v_rcp_f32_e32 v106, v106
	v_rcp_f32_e32 v107, v107
	v_rcp_f32_e32 v108, v108
	v_rcp_f32_e32 v109, v109
	v_rcp_f32_e32 v110, v110
	v_rcp_f32_e32 v111, v111
	v_mul_f32_e32 v72, v72, v104
	v_mul_f32_e32 v73, v73, v105
	v_mul_f32_e32 v74, v74, v106
	v_mul_f32_e32 v75, v75, v107
	v_mul_f32_e32 v76, v76, v108
	v_mul_f32_e32 v77, v77, v109
	v_mul_f32_e32 v78, v78, v110
	v_mul_f32_e32 v79, v79, v111
	v_mul_f32_e32 v48, v48, v96
	v_mul_f32_e32 v48, v48, v80
	v_mul_f32_e32 v48, v48, v64
	v_mul_f32_e32 v49, v49, v96
	v_mul_f32_e32 v49, v49, v81
	v_mul_f32_e32 v49, v49, v65
	v_mul_f32_e32 v50, v50, v96
	v_mul_f32_e32 v50, v50, v82
	v_mul_f32_e32 v50, v50, v66
	v_mul_f32_e32 v51, v51, v96
	v_mul_f32_e32 v51, v51, v83
	v_mul_f32_e32 v51, v51, v67
	v_mul_f32_e32 v52, v52, v96
	v_mul_f32_e32 v52, v52, v84
	v_mul_f32_e32 v52, v52, v68
	v_mul_f32_e32 v53, v53, v96
	v_mul_f32_e32 v53, v53, v85
	v_mul_f32_e32 v53, v53, v69
	v_mul_f32_e32 v54, v54, v96
	v_mul_f32_e32 v54, v54, v86
	v_mul_f32_e32 v54, v54, v70
	v_mul_f32_e32 v55, v55, v96
	v_mul_f32_e32 v55, v55, v87
	v_mul_f32_e32 v55, v55, v71
	v_mul_f32_e32 v56, v56, v96
	v_mul_f32_e32 v56, v56, v88
	v_mul_f32_e32 v56, v56, v72
	v_mul_f32_e32 v57, v57, v96
	v_mul_f32_e32 v57, v57, v89
	v_mul_f32_e32 v57, v57, v73
	v_mul_f32_e32 v58, v58, v96
	v_mul_f32_e32 v58, v58, v90
	v_mul_f32_e32 v58, v58, v74
	v_mul_f32_e32 v59, v59, v96
	v_mul_f32_e32 v59, v59, v91
	v_mul_f32_e32 v59, v59, v75
	v_mul_f32_e32 v60, v60, v96
	v_mul_f32_e32 v60, v60, v92
	v_mul_f32_e32 v60, v60, v76
	v_mul_f32_e32 v61, v61, v96
	v_mul_f32_e32 v61, v61, v93
	v_mul_f32_e32 v61, v61, v77
	v_mul_f32_e32 v62, v62, v96
	v_mul_f32_e32 v62, v62, v94
	v_mul_f32_e32 v62, v62, v78
	v_mul_f32_e32 v63, v63, v96
	v_mul_f32_e32 v63, v63, v95
	v_mul_f32_e32 v63, v63, v79
	v_cvt_pk_bf16_f32 v104, v48, v49
	v_cvt_pk_bf16_f32 v105, v50, v51
	v_cvt_pk_bf16_f32 v106, v52, v53
	v_cvt_pk_bf16_f32 v107, v54, v55
	v_cvt_pk_bf16_f32 v108, v56, v57
	v_cvt_pk_bf16_f32 v109, v58, v59
	v_cvt_pk_bf16_f32 v110, v60, v61
	v_cvt_pk_bf16_f32 v111, v62, v63
	s_lshl_b32 s0, s24, 11
	s_add_u32 s40, s92, s0
	s_addc_u32 s41, s93, 0
	global_store_dwordx4 v100, v[104:107], s[40:41]
	global_store_dwordx4 v100, v[108:111], s[40:41] offset:16
	s_cmp_lt_u32 s28, 0x8000
	s_cbranch_scc0 .Lgt_done
	s_mov_b32 s24, s28
	s_add_i32 s28, s24, s25
	s_cmp_lt_u32 s28, 0x8000
	s_cbranch_scc0 .Lgt_nopf_B
	s_lshl_b32 s0, s28, 11
	s_add_u32 s40, s14, s0
	s_addc_u32 s41, s15, 0
	global_load_dwordx4 v[0:3], v100, s[40:41]
	global_load_dwordx4 v[4:7], v100, s[40:41] offset:16
	s_mul_i32 s0, s28, 0x1a00
	s_add_u32 s40, s96, s0
	s_addc_u32 s41, s97, 0
	global_load_dwordx4 v[8:11], v100, s[40:41]
	global_load_dwordx4 v[12:15], v100, s[40:41] offset:16
	s_add_u32 s40, s40, 0x1000
	s_addc_u32 s41, s41, 0
	global_load_dwordx4 v[16:19], v100, s[40:41]
	global_load_dwordx4 v[20:23], v100, s[40:41] offset:16
	s_cmp_eq_u32 s29, 0
	s_cbranch_scc1 .Lgt_rel_B
	s_mov_b32 s29, 0
	s_waitcnt vmcnt(6)
	s_branch .Lgt_go_B

.Lgt_go_B:
	v_lshlrev_b32_e32 v48, 16, v24
	v_lshlrev_b32_e32 v96, 16, v32
	v_add_f32_e32 v48, v48, v96
	v_and_b32_e32 v49, 0xffff0000, v24
	v_and_b32_e32 v97, 0xffff0000, v32
	v_add_f32_e32 v49, v49, v97
	v_lshlrev_b32_e32 v50, 16, v25
	v_lshlrev_b32_e32 v96, 16, v33
	v_add_f32_e32 v50, v50, v96
	v_and_b32_e32 v51, 0xffff0000, v25
	v_and_b32_e32 v97, 0xffff0000, v33
	v_add_f32_e32 v51, v51, v97
	v_lshlrev_b32_e32 v52, 16, v26
	v_lshlrev_b32_e32 v96, 16, v34
	v_add_f32_e32 v52, v52, v96
	v_and_b32_e32 v53, 0xffff0000, v26
	v_and_b32_e32 v97, 0xffff0000, v34
	v_add_f32_e32 v53, v53, v97
	v_lshlrev_b32_e32 v54, 16, v27
	v_lshlrev_b32_e32 v96, 16, v35
	v_add_f32_e32 v54, v54, v96
	v_and_b32_e32 v55, 0xffff0000, v27
	v_and_b32_e32 v97, 0xffff0000, v35
	v_add_f32_e32 v55, v55, v97
	v_lshlrev_b32_e32 v56, 16, v28
	v_lshlrev_b32_e32 v96, 16, v36
	v_add_f32_e32 v56, v56, v96
	v_and_b32_e32 v57, 0xffff0000, v28
	v_and_b32_e32 v97, 0xffff0000, v36
	v_add_f32_e32 v57, v57, v97
	v_lshlrev_b32_e32 v58, 16, v29
	v_lshlrev_b32_e32 v96, 16, v37
	v_add_f32_e32 v58, v58, v96
	v_and_b32_e32 v59, 0xffff0000, v29
	v_and_b32_e32 v97, 0xffff0000, v37
	v_add_f32_e32 v59, v59, v97
	v_lshlrev_b32_e32 v60, 16, v30
	v_lshlrev_b32_e32 v96, 16, v38
	v_add_f32_e32 v60, v60, v96
	v_and_b32_e32 v61, 0xffff0000, v30
	v_and_b32_e32 v97, 0xffff0000, v38
	v_add_f32_e32 v61, v61, v97
	v_lshlrev_b32_e32 v62, 16, v31
	v_lshlrev_b32_e32 v96, 16, v39
	v_add_f32_e32 v62, v62, v96
	v_and_b32_e32 v63, 0xffff0000, v31
	v_and_b32_e32 v97, 0xffff0000, v39
	v_add_f32_e32 v63, v63, v97
	v_lshlrev_b32_e32 v64, 16, v40
	v_and_b32_e32 v65, 0xffff0000, v40
	v_lshlrev_b32_e32 v66, 16, v41
	v_and_b32_e32 v67, 0xffff0000, v41
	v_lshlrev_b32_e32 v68, 16, v42
	v_and_b32_e32 v69, 0xffff0000, v42
	v_lshlrev_b32_e32 v70, 16, v43
	v_and_b32_e32 v71, 0xffff0000, v43
	v_lshlrev_b32_e32 v72, 16, v44
	v_and_b32_e32 v73, 0xffff0000, v44
	v_lshlrev_b32_e32 v74, 16, v45
	v_and_b32_e32 v75, 0xffff0000, v45
	v_lshlrev_b32_e32 v76, 16, v46
	v_and_b32_e32 v77, 0xffff0000, v46
	v_lshlrev_b32_e32 v78, 16, v47
	v_and_b32_e32 v79, 0xffff0000, v47
	v_mul_f32_e32 v96, v48, v48
	v_mul_f32_e32 v97, v49, v49
	v_fmac_f32_e32 v96, v50, v50
	v_fmac_f32_e32 v97, v51, v51
	v_fmac_f32_e32 v96, v52, v52
	v_fmac_f32_e32 v97, v53, v53
	v_fmac_f32_e32 v96, v54, v54
	v_fmac_f32_e32 v97, v55, v55
	v_fmac_f32_e32 v96, v56, v56
	v_fmac_f32_e32 v97, v57, v57
	v_fmac_f32_e32 v96, v58, v58
	v_fmac_f32_e32 v97, v59, v59
	v_fmac_f32_e32 v96, v60, v60
	v_fmac_f32_e32 v97, v61, v61
	v_fmac_f32_e32 v96, v62, v62
	v_fmac_f32_e32 v97, v63, v63
	v_add_f32_e32 v96, v96, v97
	s_nop 1
	v_add_f32_dpp v96, v96, v96 quad_perm:[1,0,3,2] row_mask:0xf bank_mask:0xf
	s_nop 1
	v_add_f32_dpp v96, v96, v96 quad_perm:[2,3,0,1] row_mask:0xf bank_mask:0xf
	s_nop 1
	v_add_f32_dpp v96, v96, v96 row_half_mirror row_mask:0xf bank_mask:0xf
	s_nop 1
	v_add_f32_dpp v96, v96, v96 row_mirror row_mask:0xf bank_mask:0xf
	v_fmamk_f32 v96, v96, 0x3b800000, v221
	v_rsq_f32_e32 v96, v96
	v_mul_f32_e32 v104, 0xbfb8aa3b, v64
	v_mul_f32_e32 v105, 0xbfb8aa3b, v65
	v_mul_f32_e32 v106, 0xbfb8aa3b, v66
	v_mul_f32_e32 v107, 0xbfb8aa3b, v67
	v_mul_f32_e32 v108, 0xbfb8aa3b, v68
	v_mul_f32_e32 v109, 0xbfb8aa3b, v69
	v_mul_f32_e32 v110, 0xbfb8aa3b, v70
	v_mul_f32_e32 v111, 0xbfb8aa3b, v71
	v_exp_f32_e32 v104, v104
	v_exp_f32_e32 v105, v105
	v_exp_f32_e32 v106, v106
	v_exp_f32_e32 v107, v107
	v_exp_f32_e32 v108, v108
	v_exp_f32_e32 v109, v109
	v_exp_f32_e32 v110, v110
	v_exp_f32_e32 v111, v111
	v_add_f32_e32 v104, 1.0, v104
	v_add_f32_e32 v105, 1.0, v105
	v_add_f32_e32 v106, 1.0, v106
	v_add_f32_e32 v107, 1.0, v107
	v_add_f32_e32 v108, 1.0, v108
	v_add_f32_e32 v109, 1.0, v109
	v_add_f32_e32 v110, 1.0, v110
	v_add_f32_e32 v111, 1.0, v111
	v_rcp_f32_e32 v104, v104
	v_rcp_f32_e32 v105, v105
	v_rcp_f32_e32 v106, v106
	v_rcp_f32_e32 v107, v107
	v_rcp_f32_e32 v108, v108
	v_rcp_f32_e32 v109, v109
	v_rcp_f32_e32 v110, v110
	v_rcp_f32_e32 v111, v111
	v_mul_f32_e32 v64, v64, v104
	v_mul_f32_e32 v65, v65, v105
	v_mul_f32_e32 v66, v66, v106
	v_mul_f32_e32 v67, v67, v107
	v_mul_f32_e32 v68, v68, v108
	v_mul_f32_e32 v69, v69, v109
	v_mul_f32_e32 v70, v70, v110
	v_mul_f32_e32 v71, v71, v111
	v_mul_f32_e32 v104, 0xbfb8aa3b, v72
	v_mul_f32_e32 v105, 0xbfb8aa3b, v73
	v_mul_f32_e32 v106, 0xbfb8aa3b, v74
	v_mul_f32_e32 v107, 0xbfb8aa3b, v75
	v_mul_f32_e32 v108, 0xbfb8aa3b, v76
	v_mul_f32_e32 v109, 0xbfb8aa3b, v77
	v_mul_f32_e32 v110, 0xbfb8aa3b, v78
	v_mul_f32_e32 v111, 0xbfb8aa3b, v79
	v_exp_f32_e32 v104, v104
	v_exp_f32_e32 v105, v105
	v_exp_f32_e32 v106, v106
	v_exp_f32_e32 v107, v107
	v_exp_f32_e32 v108, v108
	v_exp_f32_e32 v109, v109
	v_exp_f32_e32 v110, v110
	v_exp_f32_e32 v111, v111
	v_add_f32_e32 v104, 1.0, v104
	v_add_f32_e32 v105, 1.0, v105
	v_add_f32_e32 v106, 1.0, v106
	v_add_f32_e32 v107, 1.0, v107
	v_add_f32_e32 v108, 1.0, v108
	v_add_f32_e32 v109, 1.0, v109
	v_add_f32_e32 v110, 1.0, v110
	v_add_f32_e32 v111, 1.0, v111
	v_rcp_f32_e32 v104, v104
	v_rcp_f32_e32 v105, v105
	v_rcp_f32_e32 v106, v106
	v_rcp_f32_e32 v107, v107
	v_rcp_f32_e32 v108, v108
	v_rcp_f32_e32 v109, v109
	v_rcp_f32_e32 v110, v110
	v_rcp_f32_e32 v111, v111
	v_mul_f32_e32 v72, v72, v104
	v_mul_f32_e32 v73, v73, v105
	v_mul_f32_e32 v74, v74, v106
	v_mul_f32_e32 v75, v75, v107
	v_mul_f32_e32 v76, v76, v108
	v_mul_f32_e32 v77, v77, v109
	v_mul_f32_e32 v78, v78, v110
	v_mul_f32_e32 v79, v79, v111
	v_mul_f32_e32 v48, v48, v96
	v_mul_f32_e32 v48, v48, v80
	v_mul_f32_e32 v48, v48, v64
	v_mul_f32_e32 v49, v49, v96
	v_mul_f32_e32 v49, v49, v81
	v_mul_f32_e32 v49, v49, v65
	v_mul_f32_e32 v50, v50, v96
	v_mul_f32_e32 v50, v50, v82
	v_mul_f32_e32 v50, v50, v66
	v_mul_f32_e32 v51, v51, v96
	v_mul_f32_e32 v51, v51, v83
	v_mul_f32_e32 v51, v51, v67
	v_mul_f32_e32 v52, v52, v96
	v_mul_f32_e32 v52, v52, v84
	v_mul_f32_e32 v52, v52, v68
	v_mul_f32_e32 v53, v53, v96
	v_mul_f32_e32 v53, v53, v85
	v_mul_f32_e32 v53, v53, v69
	v_mul_f32_e32 v54, v54, v96
	v_mul_f32_e32 v54, v54, v86
	v_mul_f32_e32 v54, v54, v70
	v_mul_f32_e32 v55, v55, v96
	v_mul_f32_e32 v55, v55, v87
	v_mul_f32_e32 v55, v55, v71
	v_mul_f32_e32 v56, v56, v96
	v_mul_f32_e32 v56, v56, v88
	v_mul_f32_e32 v56, v56, v72
	v_mul_f32_e32 v57, v57, v96
	v_mul_f32_e32 v57, v57, v89
	v_mul_f32_e32 v57, v57, v73
	v_mul_f32_e32 v58, v58, v96
	v_mul_f32_e32 v58, v58, v90
	v_mul_f32_e32 v58, v58, v74
	v_mul_f32_e32 v59, v59, v96
	v_mul_f32_e32 v59, v59, v91
	v_mul_f32_e32 v59, v59, v75
	v_mul_f32_e32 v60, v60, v96
	v_mul_f32_e32 v60, v60, v92
	v_mul_f32_e32 v60, v60, v76
	v_mul_f32_e32 v61, v61, v96
	v_mul_f32_e32 v61, v61, v93
	v_mul_f32_e32 v61, v61, v77
	v_mul_f32_e32 v62, v62, v96
	v_mul_f32_e32 v62, v62, v94
	v_mul_f32_e32 v62, v62, v78
	v_mul_f32_e32 v63, v63, v96
	v_mul_f32_e32 v63, v63, v95
	v_mul_f32_e32 v63, v63, v79
	v_cvt_pk_bf16_f32 v104, v48, v49
	v_cvt_pk_bf16_f32 v105, v50, v51
	v_cvt_pk_bf16_f32 v106, v52, v53
	v_cvt_pk_bf16_f32 v107, v54, v55
	v_cvt_pk_bf16_f32 v108, v56, v57
	v_cvt_pk_bf16_f32 v109, v58, v59
	v_cvt_pk_bf16_f32 v110, v60, v61
	v_cvt_pk_bf16_f32 v111, v62, v63
	s_lshl_b32 s0, s24, 11
	s_add_u32 s40, s92, s0
	s_addc_u32 s41, s93, 0
	global_store_dwordx4 v100, v[104:107], s[40:41]
	global_store_dwordx4 v100, v[108:111], s[40:41] offset:16
	s_cmp_lt_u32 s28, 0x8000
	s_cbranch_scc0 .Lgt_done
	s_mov_b32 s24, s28
	s_branch .Lgt_loop
.Lgt_done:
	v_readlane_b32 s76, v254, 11
	v_readlane_b32 s77, v254, 12
	v_readlane_b32 s78, v254, 13
	v_readlane_b32 s79, v254, 14
	v_readlane_b32 s80, v254, 15
	v_readlane_b32 s81, v254, 16
	v_readlane_b32 s90, v254, 25
	v_readlane_b32 s91, v254, 26
